# gMLP task epilogue: the 8 gain-vector pieces loaded once in a batch (were 16 serialized load-wait-store round trips)
# baseline (speedup 1.0000x reference)
.LBB0_856:
	s_or_b64 exec, exec, s[0:1]
	s_lshl_b32 s0, s5, 7
	s_waitcnt lgkmcnt(0)
	s_barrier
	ds_read_b64 v[12:13], v229 offset:63696
	s_or_b32 s0, s4, s0
	v_or_b32_e32 v14, s0, v104
	v_readlane_b32 s0, v255, 27
	v_readlane_b32 s1, v255, 28
	s_lshl_b64 s[0:1], s[0:1], 2
	v_add_u32_e32 v15, 0x400, v106
	s_waitcnt lgkmcnt(0)
	v_lshl_add_u64 v[12:13], v[12:13], 0, s[0:1]
	v_lshl_add_u64 v[12:13], v[86:87], 2, v[12:13]
	v_lshl_add_u64 v[12:13], v[12:13], 0, v[228:229]
	ds_read2_b32 v[70:71], v106 offset0:128 offset1:160
	ds_read2_b32 v[72:73], v106 offset0:192 offset1:224
	ds_read2_b32 v[78:79], v15 offset1:32
	ds_read2_b32 v[80:81], v15 offset0:64 offset1:96
	global_load_dwordx4 v[136:139], v[12:13], off offset:3072
	global_load_dwordx4 v[140:143], v[12:13], off offset:3104
	global_load_dwordx4 v[144:147], v[12:13], off offset:3136
	global_load_dwordx4 v[148:151], v[12:13], off offset:3168
	global_load_dwordx4 v[152:155], v[12:13], off offset:3200
	global_load_dwordx4 v[156:159], v[12:13], off offset:3232
	global_load_dwordx4 v[160:163], v[12:13], off offset:3264
	global_load_dwordx4 v[164:167], v[12:13], off offset:3296
	s_waitcnt vmcnt(0)
	v_mov_b32_e32 v74, v136
	v_mov_b32_e32 v75, v137
	v_mov_b32_e32 v76, v138
	v_mov_b32_e32 v77, v139
	v_lshlrev_b32_e32 v228, 11, v14
	s_waitcnt lgkmcnt(3)
	v_mov_b32_e32 v82, v71
	v_mov_b32_e32 v83, v70
	s_waitcnt lgkmcnt(2)
	v_mov_b32_e32 v70, v73
	v_mov_b32_e32 v71, v72
	v_pk_add_f32 v[70:71], v[82:83], v[70:71]
	s_waitcnt lgkmcnt(1)
	v_mov_b32_e32 v72, v79
	v_mov_b32_e32 v73, v78
	v_lshl_add_u64 v[14:15], v[88:89], 0, v[228:229]
	v_pk_add_f32 v[70:71], v[70:71], v[72:73]
	s_waitcnt lgkmcnt(0)
	v_mov_b32_e32 v72, v81
	v_mov_b32_e32 v73, v80
	v_lshlrev_b32_e32 v228, 1, v63
	v_lshl_add_u64 v[14:15], v[86:87], 1, v[14:15]
	v_pk_add_f32 v[70:71], v[70:71], v[72:73]
	v_lshl_add_u64 v[14:15], v[14:15], 0, v[228:229]
	s_mov_b64 s[0:1], 0x4ad4600
	v_pk_fma_f32 v[70:71], v[70:71], s[68:69], v[230:231] op_sel_hi:[1,0,0]
	v_lshl_add_u64 v[62:63], v[14:15], 0, s[0:1]
	v_mul_f32_e32 v72, 0x4b800000, v71
	v_cmp_gt_f32_e64 s[0:1], s92, v71
	s_mov_b32 s2, 0x7060302
	v_cmp_gt_f32_e32 vcc, s92, v70
	v_cndmask_b32_e64 v71, v71, v72, s[0:1]
	v_rsq_f32_e32 v71, v71
	s_mov_b32 s88, 0x7060302
	v_mul_f32_e32 v72, 0x45800000, v71
	v_cndmask_b32_e64 v72, v71, v72, s[0:1]
	v_pk_mul_f32 v[66:67], v[66:67], v[72:73] op_sel_hi:[1,0]
	v_pk_mul_f32 v[64:65], v[64:65], v[72:73] op_sel_hi:[1,0]
	s_mov_b32 s0, 0x4ad4000
	s_waitcnt vmcnt(0)
	v_pk_mul_f32 v[66:67], v[74:75], v[66:67]
	v_pk_mul_f32 v[64:65], v[76:77], v[64:65]
	v_bfe_u32 v74, v67, 16, 1
	v_bfe_u32 v71, v65, 16, 1
	v_bfe_u32 v73, v64, 16, 1
	v_bfe_u32 v75, v66, 16, 1
	v_add3_u32 v66, v66, v75, s89
	v_add3_u32 v67, v67, v74, s89
	v_add3_u32 v64, v64, v73, s89
	v_add3_u32 v65, v65, v71, s89
	v_perm_b32 v65, v65, v64, s2
	v_perm_b32 v64, v67, v66, s2
	v_add_co_u32_e64 v66, s[0:1], s0, v14
	v_pk_mul_f32 v[48:49], v[48:49], v[72:73] op_sel_hi:[1,0]
	s_nop 0
	v_addc_co_u32_e64 v67, s[0:1], 0, v15, s[0:1]
	global_store_dwordx2 v[66:67], v[64:65], off offset:1536
	v_mov_b32_e32 v64, v140
	v_mov_b32_e32 v65, v141
	v_mov_b32_e32 v66, v142
	v_mov_b32_e32 v67, v143
	v_pk_mul_f32 v[50:51], v[50:51], v[72:73] op_sel_hi:[1,0]
	v_pk_mul_f32 v[54:55], v[54:55], v[72:73] op_sel_hi:[1,0]
	v_pk_mul_f32 v[52:53], v[52:53], v[72:73] op_sel_hi:[1,0]
	v_pk_mul_f32 v[32:33], v[32:33], v[72:73] op_sel_hi:[1,0]
	v_pk_mul_f32 v[34:35], v[34:35], v[72:73] op_sel_hi:[1,0]
	s_mov_b64 s[0:1], 0x4ae4600
	v_pk_mul_f32 v[48:49], v[64:65], v[48:49]
	v_pk_mul_f32 v[50:51], v[66:67], v[50:51]
	v_bfe_u32 v64, v49, 16, 1
	v_bfe_u32 v65, v48, 16, 1
	v_bfe_u32 v66, v51, 16, 1
	v_bfe_u32 v67, v50, 16, 1
	v_add3_u32 v50, v50, v67, s89
	v_add3_u32 v51, v51, v66, s89
	v_add3_u32 v48, v48, v65, s89
	v_add3_u32 v49, v49, v64, s89
	v_perm_b32 v48, v49, v48, s2
	v_perm_b32 v49, v51, v50, s2
	global_store_dwordx2 v[62:63], v[48:49], off offset:16
	v_mov_b32_e32 v48, v144
	v_mov_b32_e32 v49, v145
	v_mov_b32_e32 v50, v146
	v_mov_b32_e32 v51, v147
	v_pk_mul_f32 v[48:49], v[48:49], v[54:55]
	v_pk_mul_f32 v[50:51], v[50:51], v[52:53]
	v_bfe_u32 v52, v49, 16, 1
	v_bfe_u32 v53, v48, 16, 1
	v_bfe_u32 v54, v51, 16, 1
	v_bfe_u32 v55, v50, 16, 1
	v_add3_u32 v50, v50, v55, s89
	v_add3_u32 v51, v51, v54, s89
	v_add3_u32 v48, v48, v53, s89
	v_add3_u32 v49, v49, v52, s89
	v_perm_b32 v48, v49, v48, s2
	v_perm_b32 v49, v51, v50, s2
	global_store_dwordx2 v[62:63], v[48:49], off offset:32
	v_mov_b32_e32 v48, v148
	v_mov_b32_e32 v49, v149
	v_mov_b32_e32 v50, v150
	v_mov_b32_e32 v51, v151
	v_pk_mul_f32 v[52:53], v[58:59], v[72:73] op_sel_hi:[1,0]
	v_pk_mul_f32 v[48:49], v[48:49], v[52:53]
	v_pk_mul_f32 v[52:53], v[56:57], v[72:73] op_sel_hi:[1,0]
	s_nop 0
	v_pk_mul_f32 v[50:51], v[50:51], v[52:53]
	v_bfe_u32 v52, v49, 16, 1
	v_bfe_u32 v53, v48, 16, 1
	v_bfe_u32 v54, v51, 16, 1
	v_bfe_u32 v55, v50, 16, 1
	v_add3_u32 v50, v50, v55, s89
	v_add3_u32 v51, v51, v54, s89
	v_add3_u32 v48, v48, v53, s89
	v_add3_u32 v49, v49, v52, s89
	v_perm_b32 v48, v49, v48, s2
	v_perm_b32 v49, v51, v50, s2
	global_store_dwordx2 v[62:63], v[48:49], off offset:48
	v_mov_b32_e32 v48, v152
	v_mov_b32_e32 v49, v153
	v_mov_b32_e32 v50, v154
	v_mov_b32_e32 v51, v155
	v_pk_mul_f32 v[52:53], v[60:61], v[72:73] op_sel_hi:[1,0]
	v_pk_mul_f32 v[32:33], v[32:33], v[50:51]
	v_pk_mul_f32 v[48:49], v[52:53], v[48:49]
	v_bfe_u32 v52, v33, 16, 1
	v_bfe_u32 v50, v49, 16, 1
	v_bfe_u32 v51, v48, 16, 1
	v_bfe_u32 v53, v32, 16, 1
	v_add3_u32 v53, v32, v53, s89
	v_add3_u32 v33, v33, v52, s89
	v_add3_u32 v32, v48, v51, s89
	v_add3_u32 v48, v49, v50, s89
	v_perm_b32 v32, v48, v32, s2
	v_perm_b32 v33, v33, v53, s2
	global_store_dwordx2 v[62:63], v[32:33], off offset:64
	v_mov_b32_e32 v48, v156
	v_mov_b32_e32 v49, v157
	v_mov_b32_e32 v50, v158
	v_mov_b32_e32 v51, v159
	v_pk_mul_f32 v[32:33], v[36:37], v[72:73] op_sel_hi:[1,0]
	v_pk_mul_f32 v[34:35], v[34:35], v[50:51]
	v_pk_mul_f32 v[32:33], v[32:33], v[48:49]
	v_bfe_u32 v48, v35, 16, 1
	v_bfe_u32 v36, v33, 16, 1
	v_bfe_u32 v37, v32, 16, 1
	v_bfe_u32 v49, v34, 16, 1
	v_add3_u32 v34, v34, v49, s89
	v_add3_u32 v35, v35, v48, s89
	v_add3_u32 v32, v32, v37, s89
	v_add3_u32 v33, v33, v36, s89
	v_perm_b32 v32, v33, v32, s2
	v_perm_b32 v33, v35, v34, s2
	global_store_dwordx2 v[62:63], v[32:33], off offset:80
	v_mov_b32_e32 v32, v160
	v_mov_b32_e32 v33, v161
	v_mov_b32_e32 v34, v162
	v_mov_b32_e32 v35, v163
	v_pk_mul_f32 v[36:37], v[40:41], v[72:73] op_sel_hi:[1,0]
	v_pk_mul_f32 v[32:33], v[36:37], v[32:33]
	v_pk_mul_f32 v[36:37], v[38:39], v[72:73] op_sel_hi:[1,0]
	s_nop 0
	v_pk_mul_f32 v[34:35], v[36:37], v[34:35]
	v_bfe_u32 v36, v33, 16, 1
	v_bfe_u32 v37, v32, 16, 1
	v_bfe_u32 v38, v35, 16, 1
	v_bfe_u32 v39, v34, 16, 1
	v_add3_u32 v34, v34, v39, s89
	v_add3_u32 v35, v35, v38, s89
	v_add3_u32 v32, v32, v37, s89
	v_add3_u32 v33, v33, v36, s89
	v_perm_b32 v32, v33, v32, s2
	v_perm_b32 v33, v35, v34, s2
	global_store_dwordx2 v[62:63], v[32:33], off offset:96
	v_mov_b32_e32 v32, v164
	v_mov_b32_e32 v33, v165
	v_mov_b32_e32 v34, v166
	v_mov_b32_e32 v35, v167
	v_pk_mul_f32 v[36:37], v[42:43], v[72:73] op_sel_hi:[1,0]
	v_pk_mul_f32 v[32:33], v[36:37], v[32:33]
	v_pk_mul_f32 v[36:37], v[44:45], v[72:73] op_sel_hi:[1,0]
	s_nop 0
	v_pk_mul_f32 v[34:35], v[36:37], v[34:35]
	v_bfe_u32 v36, v33, 16, 1
	v_bfe_u32 v37, v32, 16, 1
	v_bfe_u32 v38, v35, 16, 1
	v_bfe_u32 v39, v34, 16, 1
	v_add3_u32 v34, v34, v39, s89
	v_add3_u32 v35, v35, v38, s89
	v_add3_u32 v32, v32, v37, s89
	v_add3_u32 v33, v33, v36, s89
	v_perm_b32 v32, v33, v32, s2
	v_perm_b32 v33, v35, v34, s2
	global_store_dwordx2 v[62:63], v[32:33], off offset:112
	v_mov_b32_e32 v34, v136
	v_mov_b32_e32 v35, v137
	v_mov_b32_e32 v36, v138
	v_mov_b32_e32 v37, v139
	v_mul_f32_e32 v32, 0x4b800000, v70
	v_cndmask_b32_e32 v32, v70, v32, vcc
	v_rsq_f32_e32 v32, v32
	s_nop 0
	v_mul_f32_e32 v33, 0x45800000, v32
	v_cndmask_b32_e32 v32, v32, v33, vcc
	v_pk_mul_f32 v[16:17], v[16:17], v[32:33] op_sel_hi:[1,0]
	v_pk_mul_f32 v[18:19], v[18:19], v[32:33] op_sel_hi:[1,0]
	v_pk_mul_f32 v[16:17], v[34:35], v[16:17]
	v_pk_mul_f32 v[18:19], v[36:37], v[18:19]
	v_bfe_u32 v33, v17, 16, 1
	v_bfe_u32 v34, v16, 16, 1
	v_bfe_u32 v36, v18, 16, 1
	v_add3_u32 v16, v16, v34, s89
	v_add3_u32 v17, v17, v33, s89
	v_bfe_u32 v35, v19, 16, 1
	v_add3_u32 v36, v18, v36, s89
	v_perm_b32 v18, v17, v16, s2
	v_lshl_add_u64 v[16:17], v[14:15], 0, s[0:1]
	s_mov_b32 s0, 0x4ae4000
	v_add3_u32 v19, v19, v35, s89
	v_add_co_u32_e32 v14, vcc, s0, v14
	v_perm_b32 v19, v19, v36, s2
	s_nop 0
	v_addc_co_u32_e32 v15, vcc, 0, v15, vcc
	global_store_dwordx2 v[14:15], v[18:19], off offset:1536
	v_mov_b32_e32 v34, v140
	v_mov_b32_e32 v35, v141
	v_mov_b32_e32 v36, v142
	v_mov_b32_e32 v37, v143
	v_pk_mul_f32 v[14:15], v[20:21], v[32:33] op_sel_hi:[1,0]
	v_pk_mul_f32 v[18:19], v[22:23], v[32:33] op_sel_hi:[1,0]
	v_pk_mul_f32 v[4:5], v[4:5], v[32:33] op_sel_hi:[1,0]
	v_pk_mul_f32 v[6:7], v[6:7], v[32:33] op_sel_hi:[1,0]
	v_pk_mul_f32 v[8:9], v[8:9], v[32:33] op_sel_hi:[1,0]
	v_pk_mul_f32 v[0:1], v[0:1], v[32:33] op_sel_hi:[1,0]
	v_pk_mul_f32 v[2:3], v[2:3], v[32:33] op_sel_hi:[1,0]
	s_mov_b64 s[0:1], 0
	v_pk_mul_f32 v[14:15], v[34:35], v[14:15]
	v_pk_mul_f32 v[18:19], v[36:37], v[18:19]
	v_bfe_u32 v20, v15, 16, 1
	v_bfe_u32 v21, v14, 16, 1
	v_bfe_u32 v22, v19, 16, 1
	v_bfe_u32 v23, v18, 16, 1
	v_add3_u32 v18, v18, v23, s89
	v_add3_u32 v19, v19, v22, s89
	v_add3_u32 v14, v14, v21, s89
	v_add3_u32 v15, v15, v20, s89
	v_perm_b32 v14, v15, v14, s2
	v_perm_b32 v15, v19, v18, s2
	global_store_dwordx2 v[16:17], v[14:15], off offset:16
	v_mov_b32_e32 v18, v144
	v_mov_b32_e32 v19, v145
	v_mov_b32_e32 v20, v146
	v_mov_b32_e32 v21, v147
	v_pk_mul_f32 v[14:15], v[24:25], v[32:33] op_sel_hi:[1,0]
	v_pk_mul_f32 v[14:15], v[18:19], v[14:15]
	v_pk_mul_f32 v[18:19], v[26:27], v[32:33] op_sel_hi:[1,0]
	s_nop 0
	v_pk_mul_f32 v[18:19], v[20:21], v[18:19]
	v_bfe_u32 v20, v15, 16, 1
	v_bfe_u32 v21, v14, 16, 1
	v_bfe_u32 v22, v19, 16, 1
	v_bfe_u32 v23, v18, 16, 1
	v_add3_u32 v18, v18, v23, s89
	v_add3_u32 v19, v19, v22, s89
	v_add3_u32 v14, v14, v21, s89
	v_add3_u32 v15, v15, v20, s89
	v_perm_b32 v14, v15, v14, s2
	v_perm_b32 v15, v19, v18, s2
	global_store_dwordx2 v[16:17], v[14:15], off offset:32
	v_mov_b32_e32 v18, v148
	v_mov_b32_e32 v19, v149
	v_mov_b32_e32 v20, v150
	v_mov_b32_e32 v21, v151
	v_pk_mul_f32 v[14:15], v[28:29], v[32:33] op_sel_hi:[1,0]
	v_pk_mul_f32 v[14:15], v[18:19], v[14:15]
	v_pk_mul_f32 v[18:19], v[30:31], v[32:33] op_sel_hi:[1,0]
	s_nop 0
	v_pk_mul_f32 v[18:19], v[20:21], v[18:19]
	v_bfe_u32 v20, v15, 16, 1
	v_bfe_u32 v21, v14, 16, 1
	v_bfe_u32 v22, v19, 16, 1
	v_bfe_u32 v23, v18, 16, 1
	v_add3_u32 v18, v18, v23, s89
	v_add3_u32 v19, v19, v22, s89
	v_add3_u32 v14, v14, v21, s89
	v_add3_u32 v15, v15, v20, s89
	v_perm_b32 v14, v15, v14, s2
	v_perm_b32 v15, v19, v18, s2
	global_store_dwordx2 v[16:17], v[14:15], off offset:48
	v_mov_b32_e32 v18, v152
	v_mov_b32_e32 v19, v153
	v_mov_b32_e32 v20, v154
	v_mov_b32_e32 v21, v155
	v_pk_mul_f32 v[14:15], v[46:47], v[32:33] op_sel_hi:[1,0]
	v_pk_mul_f32 v[14:15], v[14:15], v[18:19]
	v_pk_mul_f32 v[18:19], v[68:69], v[32:33] op_sel_hi:[1,0]
	s_nop 0
	v_pk_mul_f32 v[18:19], v[18:19], v[20:21]
	v_bfe_u32 v20, v15, 16, 1
	v_bfe_u32 v21, v14, 16, 1
	v_bfe_u32 v22, v19, 16, 1
	v_bfe_u32 v23, v18, 16, 1
	v_add3_u32 v18, v18, v23, s89
	v_add3_u32 v19, v19, v22, s89
	v_add3_u32 v14, v14, v21, s89
	v_add3_u32 v15, v15, v20, s89
	v_perm_b32 v14, v15, v14, s2
	v_perm_b32 v15, v19, v18, s2
	global_store_dwordx2 v[16:17], v[14:15], off offset:64
	v_mov_b32_e32 v18, v156
	v_mov_b32_e32 v19, v157
	v_mov_b32_e32 v20, v158
	v_mov_b32_e32 v21, v159
	v_pk_mul_f32 v[4:5], v[4:5], v[18:19]
	v_pk_mul_f32 v[6:7], v[6:7], v[20:21]
	v_bfe_u32 v14, v5, 16, 1
	v_bfe_u32 v15, v4, 16, 1
	v_bfe_u32 v18, v7, 16, 1
	v_bfe_u32 v19, v6, 16, 1
	v_add3_u32 v6, v6, v19, s89
	v_add3_u32 v7, v7, v18, s89
	v_add3_u32 v4, v4, v15, s89
	v_add3_u32 v5, v5, v14, s89
	v_perm_b32 v4, v5, v4, s2
	v_perm_b32 v5, v7, v6, s2
	global_store_dwordx2 v[16:17], v[4:5], off offset:80
	v_mov_b32_e32 v4, v160
	v_mov_b32_e32 v5, v161
	v_mov_b32_e32 v6, v162
	v_mov_b32_e32 v7, v163
	v_pk_mul_f32 v[4:5], v[8:9], v[4:5]
	v_pk_mul_f32 v[8:9], v[10:11], v[32:33] op_sel_hi:[1,0]
	s_nop 0
	v_pk_mul_f32 v[6:7], v[8:9], v[6:7]
	v_bfe_u32 v8, v5, 16, 1
	v_bfe_u32 v9, v4, 16, 1
	v_bfe_u32 v10, v7, 16, 1
	v_bfe_u32 v11, v6, 16, 1
	v_add3_u32 v6, v6, v11, s89
	v_add3_u32 v7, v7, v10, s89
	v_add3_u32 v4, v4, v9, s89
	v_add3_u32 v5, v5, v8, s89
	v_perm_b32 v4, v5, v4, s2
	v_perm_b32 v5, v7, v6, s2
	global_store_dwordx2 v[16:17], v[4:5], off offset:96
	v_mov_b32_e32 v4, v164
	v_mov_b32_e32 v5, v165
	v_mov_b32_e32 v6, v166
	v_mov_b32_e32 v7, v167
	v_pk_mul_f32 v[0:1], v[0:1], v[4:5]
	v_pk_mul_f32 v[2:3], v[2:3], v[6:7]
	v_bfe_u32 v4, v1, 16, 1
	v_bfe_u32 v5, v0, 16, 1
	v_bfe_u32 v6, v3, 16, 1
	v_bfe_u32 v7, v2, 16, 1
	v_add3_u32 v2, v2, v7, s89
	v_add3_u32 v3, v3, v6, s89
	v_add3_u32 v0, v0, v5, s89
	v_add3_u32 v1, v1, v4, s89
	v_perm_b32 v0, v1, v0, s2
	v_perm_b32 v1, v3, v2, s2
	global_store_dwordx2 v[16:17], v[0:1], off offset:112
	s_barrier
